# v12 plus split-K of the in-proj tail round: workgroup pairs share a tile, each accumulates half of K, partial sums handed over through d_ws with a counter flag
# baseline (speedup 1.0000x reference)
.LBB0_267:
	s_nop 0
	v_cndmask_b32_e64 v0, 0, 1, s[42:43]
	v_cmp_ne_u32_e64 s[40:41], 1, v0
	s_andn2_b64 vcc, exec, s[42:43]
	s_mov_b32 s25, s45
	s_cbranch_vccnz .LBB0_269
	s_mul_i32 s2, s23, s65
	s_mul_i32 s3, s72, s86
	s_add_i32 s25, s3, s2
	s_lshr_b32 s32, s86, 2
	s_sub_i32 s32, s32, 1
	s_max_i32 s32, s32, 0
	s_lshl_b32 s32, s32, 8
	s_cmp_eq_u32 s16, 3
	s_cselect_b32 s32, s32, 0
	s_add_i32 s25, s25, s32
	s_cmp_eq_u32 s24, 18
	s_cbranch_scc0 .Lsk_b
	s_cmp_eq_u32 s80, 0x100
	s_cbranch_scc0 .Lsk_b
	s_cmp_eq_u32 s0, 4
	s_cbranch_scc0 .Lsk_b
	s_cmp_lt_u32 s12, 0x80
	s_cbranch_scc1 .Lsk_b
	s_addk_i32 s25, 0x800

.Lkt_nt:
	s_add_i32 s100, s101, -2
	s_cmp_eq_u32 s24, 18
	s_cbranch_scc0 .Lsk_c
	s_cmp_eq_u32 s80, 0x100
	s_cbranch_scc0 .Lsk_c
	s_cmp_eq_u32 s0, 4
	s_cbranch_scc0 .Lsk_c
	s_cmp_lt_u32 s12, 0x80
	s_cbranch_scc1 .Lsk_c
	s_addk_i32 s22, 0x800
.Lsk_c:
	s_cmp_eq_u32 s24, 18
	s_cbranch_scc0 .Lsk_d
	s_cmp_eq_u32 s80, 0x100
	s_cbranch_scc0 .Lsk_d
	s_cmp_eq_u32 s0, 5
	s_cbranch_scc0 .Lsk_d
	s_movk_i32 s101, 16
	s_movk_i32 s100, 14
.Lsk_d:
	s_and_b64 s[2:3], s[42:43], exec
	v_mov_b32_e32 v0, 0
	s_cselect_b32 s2, s22, s44
	s_add_i32 s3, s45, 0x80
	s_add_i32 s42, s44, 0x100
	s_mov_b32 s43, 0
	v_mov_b32_e32 v1, v0
	v_mov_b32_e32 v2, v0
	v_mov_b32_e32 v3, v0
	v_mov_b32_e32 v4, v0
	v_mov_b32_e32 v5, v0
	v_mov_b32_e32 v6, v0
	v_mov_b32_e32 v7, v0
	v_mov_b32_e32 v16, v0
	v_mov_b32_e32 v17, v0
	v_mov_b32_e32 v18, v0
	v_mov_b32_e32 v19, v0
	v_mov_b32_e32 v20, v0
	v_mov_b32_e32 v21, v0
	v_mov_b32_e32 v22, v0
	v_mov_b32_e32 v23, v0
	v_mov_b32_e32 v32, v0
	v_mov_b32_e32 v33, v0
	v_mov_b32_e32 v34, v0
	v_mov_b32_e32 v35, v0
	v_mov_b32_e32 v36, v0
	v_mov_b32_e32 v37, v0
	v_mov_b32_e32 v38, v0
	v_mov_b32_e32 v39, v0
	v_mov_b32_e32 v48, v0
	v_mov_b32_e32 v49, v0
	v_mov_b32_e32 v50, v0
	v_mov_b32_e32 v51, v0
	v_mov_b32_e32 v52, v0
	v_mov_b32_e32 v53, v0
	v_mov_b32_e32 v54, v0
	v_mov_b32_e32 v55, v0
	v_mov_b32_e32 v8, v0
	v_mov_b32_e32 v9, v0
	v_mov_b32_e32 v10, v0
	v_mov_b32_e32 v11, v0
	v_mov_b32_e32 v12, v0
	v_mov_b32_e32 v13, v0
	v_mov_b32_e32 v14, v0
	v_mov_b32_e32 v15, v0
	v_mov_b32_e32 v24, v0
	v_mov_b32_e32 v25, v0
	v_mov_b32_e32 v26, v0
	v_mov_b32_e32 v27, v0
	v_mov_b32_e32 v28, v0
	v_mov_b32_e32 v29, v0
	v_mov_b32_e32 v30, v0
	v_mov_b32_e32 v31, v0
	v_mov_b32_e32 v40, v0
	v_mov_b32_e32 v41, v0
	v_mov_b32_e32 v42, v0
	v_mov_b32_e32 v43, v0
	v_mov_b32_e32 v44, v0
	v_mov_b32_e32 v45, v0
	v_mov_b32_e32 v46, v0
	v_mov_b32_e32 v47, v0
	v_mov_b32_e32 v56, v0
	v_mov_b32_e32 v57, v0
	v_mov_b32_e32 v58, v0
	v_mov_b32_e32 v59, v0
	v_mov_b32_e32 v60, v0
	v_mov_b32_e32 v61, v0
	v_mov_b32_e32 v62, v0
	v_mov_b32_e32 v63, v0
	v_mov_b32_e32 v64, v0
	v_mov_b32_e32 v65, v0
	v_mov_b32_e32 v66, v0
	v_mov_b32_e32 v67, v0
	v_mov_b32_e32 v68, v0
	v_mov_b32_e32 v69, v0
	v_mov_b32_e32 v70, v0
	v_mov_b32_e32 v71, v0
	v_mov_b32_e32 v80, v0
	v_mov_b32_e32 v81, v0
	v_mov_b32_e32 v82, v0
	v_mov_b32_e32 v83, v0
	v_mov_b32_e32 v84, v0
	v_mov_b32_e32 v85, v0
	v_mov_b32_e32 v86, v0
	v_mov_b32_e32 v87, v0
	v_mov_b32_e32 v96, v0
	v_mov_b32_e32 v97, v0
	v_mov_b32_e32 v98, v0
	v_mov_b32_e32 v99, v0
	v_mov_b32_e32 v100, v0
	v_mov_b32_e32 v101, v0
	v_mov_b32_e32 v102, v0
	v_mov_b32_e32 v103, v0
	v_mov_b32_e32 v112, v0
	v_mov_b32_e32 v113, v0
	v_mov_b32_e32 v114, v0
	v_mov_b32_e32 v115, v0
	v_mov_b32_e32 v116, v0
	v_mov_b32_e32 v117, v0
	v_mov_b32_e32 v118, v0
	v_mov_b32_e32 v119, v0
	v_mov_b32_e32 v72, v0
	v_mov_b32_e32 v73, v0
	v_mov_b32_e32 v74, v0
	v_mov_b32_e32 v75, v0
	v_mov_b32_e32 v76, v0
	v_mov_b32_e32 v77, v0
	v_mov_b32_e32 v78, v0
	v_mov_b32_e32 v79, v0
	v_mov_b32_e32 v88, v0
	v_mov_b32_e32 v89, v0
	v_mov_b32_e32 v90, v0
	v_mov_b32_e32 v91, v0
	v_mov_b32_e32 v92, v0
	v_mov_b32_e32 v93, v0
	v_mov_b32_e32 v94, v0
	v_mov_b32_e32 v95, v0
	v_mov_b32_e32 v104, v0
	v_mov_b32_e32 v105, v0
	v_mov_b32_e32 v106, v0
	v_mov_b32_e32 v107, v0
	v_mov_b32_e32 v108, v0
	v_mov_b32_e32 v109, v0
	v_mov_b32_e32 v110, v0
	v_mov_b32_e32 v111, v0
	v_mov_b32_e32 v120, v0
	v_mov_b32_e32 v121, v0
	v_mov_b32_e32 v122, v0
	v_mov_b32_e32 v123, v0
	v_mov_b32_e32 v124, v0
	v_mov_b32_e32 v125, v0
	v_mov_b32_e32 v126, v0
	v_mov_b32_e32 v127, v0

.LBB0_273:
	s_cmp_eq_u32 s24, 18
	s_cbranch_scc0 .Lsk_none
	s_cmp_eq_u32 s80, 0x100
	s_cbranch_scc0 .Lsk_none
	s_cmp_eq_u32 s0, 5
	s_cbranch_scc0 .Lsk_none
	s_sub_u32 s2, s30, 0x28700000
	s_subb_u32 s3, s31, 0
	v_readfirstlane_b32 s50, v160
	s_lshr_b32 s50, s50, 6
	s_and_b32 s51, s12, 0x7f
	v_lshlrev_b32_e32 v250, 4, v197
	v_mov_b32_e32 v251, 1
	s_lshl_b32 s90, s51, 18
	s_lshl_b32 s91, s50, 15
	s_add_u32 s90, s90, s91
	s_add_u32 s90, s90, 0x1fb00000
	s_lshl_b32 s51, s51, 2
	s_add_u32 s100, s2, s90
	s_addc_u32 s101, s3, 0
	s_add_u32 s2, s2, s51
	s_addc_u32 s3, s3, 0
	s_add_u32 s2, s2, 0x8000
	s_addc_u32 s3, s3, 0
	s_cmp_lt_u32 s12, 0x80
	s_cbranch_scc1 .Lsk_owner
	global_store_dwordx4 v250, v[0:3], s[100:101]
	global_store_dwordx4 v250, v[4:7], s[100:101] offset:1024
	global_store_dwordx4 v250, v[8:11], s[100:101] offset:2048
	global_store_dwordx4 v250, v[12:15], s[100:101] offset:3072
	s_add_u32 s100, s100, 0x1000
	s_addc_u32 s101, s101, 0
	global_store_dwordx4 v250, v[16:19], s[100:101]
	global_store_dwordx4 v250, v[20:23], s[100:101] offset:1024
	global_store_dwordx4 v250, v[24:27], s[100:101] offset:2048
	global_store_dwordx4 v250, v[28:31], s[100:101] offset:3072
	s_add_u32 s100, s100, 0x1000
	s_addc_u32 s101, s101, 0
	global_store_dwordx4 v250, v[32:35], s[100:101]
	global_store_dwordx4 v250, v[36:39], s[100:101] offset:1024
	global_store_dwordx4 v250, v[40:43], s[100:101] offset:2048
	global_store_dwordx4 v250, v[44:47], s[100:101] offset:3072
	s_add_u32 s100, s100, 0x1000
	s_addc_u32 s101, s101, 0
	global_store_dwordx4 v250, v[48:51], s[100:101]
	global_store_dwordx4 v250, v[52:55], s[100:101] offset:1024
	global_store_dwordx4 v250, v[56:59], s[100:101] offset:2048
	global_store_dwordx4 v250, v[60:63], s[100:101] offset:3072
	s_add_u32 s100, s100, 0x1000
	s_addc_u32 s101, s101, 0
	global_store_dwordx4 v250, v[64:67], s[100:101]
	global_store_dwordx4 v250, v[68:71], s[100:101] offset:1024
	global_store_dwordx4 v250, v[72:75], s[100:101] offset:2048
	global_store_dwordx4 v250, v[76:79], s[100:101] offset:3072
	s_add_u32 s100, s100, 0x1000
	s_addc_u32 s101, s101, 0
	global_store_dwordx4 v250, v[80:83], s[100:101]
	global_store_dwordx4 v250, v[84:87], s[100:101] offset:1024
	global_store_dwordx4 v250, v[88:91], s[100:101] offset:2048
	global_store_dwordx4 v250, v[92:95], s[100:101] offset:3072
	s_add_u32 s100, s100, 0x1000
	s_addc_u32 s101, s101, 0
	global_store_dwordx4 v250, v[96:99], s[100:101]
	global_store_dwordx4 v250, v[100:103], s[100:101] offset:1024
	global_store_dwordx4 v250, v[104:107], s[100:101] offset:2048
	global_store_dwordx4 v250, v[108:111], s[100:101] offset:3072
	s_add_u32 s100, s100, 0x1000
	s_addc_u32 s101, s101, 0
	global_store_dwordx4 v250, v[112:115], s[100:101]
	global_store_dwordx4 v250, v[116:119], s[100:101] offset:1024
	global_store_dwordx4 v250, v[120:123], s[100:101] offset:2048
	global_store_dwordx4 v250, v[124:127], s[100:101] offset:3072
	s_waitcnt vmcnt(0)
	s_barrier
	s_cmp_eq_u32 s50, 0
	s_cbranch_scc0 .LBB0_492
	buffer_wbl2 sc1
	s_waitcnt vmcnt(0)
	s_mov_b64 s[90:91], exec
	s_mov_b64 exec, 1
	global_atomic_add v157, v251, s[2:3]
	s_mov_b64 exec, s[90:91]
	s_waitcnt vmcnt(0)
	s_branch .LBB0_492
.Lsk_owner:
	v_readlane_b32 s90, v254, 22
	s_mov_b32 s91, 0
	s_add_u32 s90, s90, 1
.Lsk_spin:
	global_load_dword v251, v157, s[2:3] sc1
	s_waitcnt vmcnt(0)
	v_readfirstlane_b32 s32, v251
	s_cmp_ge_u32 s32, s90
	s_cbranch_scc1 .Lsk_go
	s_sleep 1
	s_add_u32 s91, s91, 1
	s_cmp_lt_u32 s91, 0x4000
	s_cbranch_scc1 .Lsk_spin
.Lsk_go:
	buffer_inv sc1
	s_waitcnt vmcnt(0)
	global_load_dwordx4 v[232:235], v250, s[100:101]
	global_load_dwordx4 v[236:239], v250, s[100:101] offset:1024
	global_load_dwordx4 v[240:243], v250, s[100:101] offset:2048
	global_load_dwordx4 v[244:247], v250, s[100:101] offset:3072
	s_add_u32 s100, s100, 0x1000
	s_addc_u32 s101, s101, 0
	s_waitcnt vmcnt(0)
	v_pk_add_f32 v[0:1], v[0:1], v[232:233]
	v_pk_add_f32 v[2:3], v[2:3], v[234:235]
	v_pk_add_f32 v[4:5], v[4:5], v[236:237]
	v_pk_add_f32 v[6:7], v[6:7], v[238:239]
	v_pk_add_f32 v[8:9], v[8:9], v[240:241]
	v_pk_add_f32 v[10:11], v[10:11], v[242:243]
	v_pk_add_f32 v[12:13], v[12:13], v[244:245]
	v_pk_add_f32 v[14:15], v[14:15], v[246:247]
	global_load_dwordx4 v[232:235], v250, s[100:101]
	global_load_dwordx4 v[236:239], v250, s[100:101] offset:1024
	global_load_dwordx4 v[240:243], v250, s[100:101] offset:2048
	global_load_dwordx4 v[244:247], v250, s[100:101] offset:3072
	s_add_u32 s100, s100, 0x1000
	s_addc_u32 s101, s101, 0
	s_waitcnt vmcnt(0)
	v_pk_add_f32 v[16:17], v[16:17], v[232:233]
	v_pk_add_f32 v[18:19], v[18:19], v[234:235]
	v_pk_add_f32 v[20:21], v[20:21], v[236:237]
	v_pk_add_f32 v[22:23], v[22:23], v[238:239]
	v_pk_add_f32 v[24:25], v[24:25], v[240:241]
	v_pk_add_f32 v[26:27], v[26:27], v[242:243]
	v_pk_add_f32 v[28:29], v[28:29], v[244:245]
	v_pk_add_f32 v[30:31], v[30:31], v[246:247]
	global_load_dwordx4 v[232:235], v250, s[100:101]
	global_load_dwordx4 v[236:239], v250, s[100:101] offset:1024
	global_load_dwordx4 v[240:243], v250, s[100:101] offset:2048
	global_load_dwordx4 v[244:247], v250, s[100:101] offset:3072
	s_add_u32 s100, s100, 0x1000
	s_addc_u32 s101, s101, 0
	s_waitcnt vmcnt(0)
	v_pk_add_f32 v[32:33], v[32:33], v[232:233]
	v_pk_add_f32 v[34:35], v[34:35], v[234:235]
	v_pk_add_f32 v[36:37], v[36:37], v[236:237]
	v_pk_add_f32 v[38:39], v[38:39], v[238:239]
	v_pk_add_f32 v[40:41], v[40:41], v[240:241]
	v_pk_add_f32 v[42:43], v[42:43], v[242:243]
	v_pk_add_f32 v[44:45], v[44:45], v[244:245]
	v_pk_add_f32 v[46:47], v[46:47], v[246:247]
	global_load_dwordx4 v[232:235], v250, s[100:101]
	global_load_dwordx4 v[236:239], v250, s[100:101] offset:1024
	global_load_dwordx4 v[240:243], v250, s[100:101] offset:2048
	global_load_dwordx4 v[244:247], v250, s[100:101] offset:3072
	s_add_u32 s100, s100, 0x1000
	s_addc_u32 s101, s101, 0
	s_waitcnt vmcnt(0)
	v_pk_add_f32 v[48:49], v[48:49], v[232:233]
	v_pk_add_f32 v[50:51], v[50:51], v[234:235]
	v_pk_add_f32 v[52:53], v[52:53], v[236:237]
	v_pk_add_f32 v[54:55], v[54:55], v[238:239]
	v_pk_add_f32 v[56:57], v[56:57], v[240:241]
	v_pk_add_f32 v[58:59], v[58:59], v[242:243]
	v_pk_add_f32 v[60:61], v[60:61], v[244:245]
	v_pk_add_f32 v[62:63], v[62:63], v[246:247]
	global_load_dwordx4 v[232:235], v250, s[100:101]
	global_load_dwordx4 v[236:239], v250, s[100:101] offset:1024
	global_load_dwordx4 v[240:243], v250, s[100:101] offset:2048
	global_load_dwordx4 v[244:247], v250, s[100:101] offset:3072
	s_add_u32 s100, s100, 0x1000
	s_addc_u32 s101, s101, 0
	s_waitcnt vmcnt(0)
	v_pk_add_f32 v[64:65], v[64:65], v[232:233]
	v_pk_add_f32 v[66:67], v[66:67], v[234:235]
	v_pk_add_f32 v[68:69], v[68:69], v[236:237]
	v_pk_add_f32 v[70:71], v[70:71], v[238:239]
	v_pk_add_f32 v[72:73], v[72:73], v[240:241]
	v_pk_add_f32 v[74:75], v[74:75], v[242:243]
	v_pk_add_f32 v[76:77], v[76:77], v[244:245]
	v_pk_add_f32 v[78:79], v[78:79], v[246:247]
	global_load_dwordx4 v[232:235], v250, s[100:101]
	global_load_dwordx4 v[236:239], v250, s[100:101] offset:1024
	global_load_dwordx4 v[240:243], v250, s[100:101] offset:2048
	global_load_dwordx4 v[244:247], v250, s[100:101] offset:3072
	s_add_u32 s100, s100, 0x1000
	s_addc_u32 s101, s101, 0
	s_waitcnt vmcnt(0)
	v_pk_add_f32 v[80:81], v[80:81], v[232:233]
	v_pk_add_f32 v[82:83], v[82:83], v[234:235]
	v_pk_add_f32 v[84:85], v[84:85], v[236:237]
	v_pk_add_f32 v[86:87], v[86:87], v[238:239]
	v_pk_add_f32 v[88:89], v[88:89], v[240:241]
	v_pk_add_f32 v[90:91], v[90:91], v[242:243]
	v_pk_add_f32 v[92:93], v[92:93], v[244:245]
	v_pk_add_f32 v[94:95], v[94:95], v[246:247]
	global_load_dwordx4 v[232:235], v250, s[100:101]
	global_load_dwordx4 v[236:239], v250, s[100:101] offset:1024
	global_load_dwordx4 v[240:243], v250, s[100:101] offset:2048
	global_load_dwordx4 v[244:247], v250, s[100:101] offset:3072
	s_add_u32 s100, s100, 0x1000
	s_addc_u32 s101, s101, 0
	s_waitcnt vmcnt(0)
	v_pk_add_f32 v[96:97], v[96:97], v[232:233]
	v_pk_add_f32 v[98:99], v[98:99], v[234:235]
	v_pk_add_f32 v[100:101], v[100:101], v[236:237]
	v_pk_add_f32 v[102:103], v[102:103], v[238:239]
	v_pk_add_f32 v[104:105], v[104:105], v[240:241]
	v_pk_add_f32 v[106:107], v[106:107], v[242:243]
	v_pk_add_f32 v[108:109], v[108:109], v[244:245]
	v_pk_add_f32 v[110:111], v[110:111], v[246:247]
	global_load_dwordx4 v[232:235], v250, s[100:101]
	global_load_dwordx4 v[236:239], v250, s[100:101] offset:1024
	global_load_dwordx4 v[240:243], v250, s[100:101] offset:2048
	global_load_dwordx4 v[244:247], v250, s[100:101] offset:3072
	s_add_u32 s100, s100, 0x1000
	s_addc_u32 s101, s101, 0
	s_waitcnt vmcnt(0)
	v_pk_add_f32 v[112:113], v[112:113], v[232:233]
	v_pk_add_f32 v[114:115], v[114:115], v[234:235]
	v_pk_add_f32 v[116:117], v[116:117], v[236:237]
	v_pk_add_f32 v[118:119], v[118:119], v[238:239]
	v_pk_add_f32 v[120:121], v[120:121], v[240:241]
	v_pk_add_f32 v[122:123], v[122:123], v[242:243]
	v_pk_add_f32 v[124:125], v[124:125], v[244:245]
	v_pk_add_f32 v[126:127], v[126:127], v[246:247]
